# GEMM tiles: first K-iteration peeled (C=0 first MFMAs, no 128-mov clearing, no vmcnt(0) before the K-loop, first-two waits do not wait on previous tile stores); RESID/other epilogue flat stores made g
# speedup vs baseline: 1.0157x; 1.0018x over previous
.LBB0_419:
	s_add_i32 m0, s11, 0x18000
	v_lshl_add_u64 v[8:9], v[8:9], 0, s[60:61]
	s_waitcnt vmcnt(2)
	s_barrier
	global_load_lds_dwordx4 v[8:9], off
	v_lshl_add_u64 v[4:5], v[4:5], 0, s[60:61]
	s_add_i32 m0, s11, 0x1a000
	s_add_i32 s31, s11, 0x8000
	global_load_lds_dwordx4 v[4:5], off
	v_lshl_add_u64 v[4:5], v[6:7], 0, s[60:61]
	s_mov_b32 m0, s31
	s_add_i32 s18, s11, 0xa000
	global_load_lds_dwordx4 v[4:5], off
	v_lshl_add_u64 v[4:5], v[10:11], 0, s[60:61]
	s_mov_b32 m0, s18
	v_lshl_add_u64 v[2:3], v[2:3], 0, s[60:61]
	global_load_lds_dwordx4 v[4:5], off
	s_add_i32 m0, s11, 0x1c000
	v_lshl_add_u64 v[0:1], v[0:1], 0, s[60:61]
	global_load_lds_dwordx4 v[2:3], off
	s_add_i32 m0, s11, 0x1e000
	s_movk_i32 s21, 0x3c0
	global_load_lds_dwordx4 v[0:1], off
	v_and_b32_e32 v0, 48, v196
	v_lshlrev_b32_e32 v1, 6, v196
	s_and_b32 s17, s17, 3
	v_and_or_b32 v0, v1, s21, v0
	v_lshlrev_b32_e32 v1, 2, v196
	s_lshl_b32 s19, s20, 6
	s_lshl_b32 s20, s20, 13
	v_and_b32_e32 v1, 32, v1
	s_lshl_b32 s21, s17, 12
	v_bitop3_b32 v2, v0, s20, v1 bitop3:0xde
	s_lshl_b32 s20, s17, 5
	v_bitop3_b32 v186, s21, v0, v1 bitop3:0xf6
	s_add_i32 s21, s88, -2
	s_cmpk_lt_u32 s16, 0x100
	s_cselect_b64 s[28:29], -1, 0
	s_cmp_eq_u32 s17, 0
	s_cselect_b64 s[0:1], -1, 0
	v_writelane_b32 v255, s0, 26
	s_lshl_b32 s91, s17, 1
	s_ashr_i32 s89, s72, 31
	v_writelane_b32 v255, s1, 27
	s_lshr_b32 s0, s22, 3
	s_ashr_i32 s87, s66, 31
	s_and_b32 s86, s22, 4
	v_writelane_b32 v255, s0, 28
	s_add_i32 s0, s0, 1
	s_lshr_b32 s64, s58, 6
	s_and_b64 s[2:3], s[2:3], exec
	v_cvt_f32_u32_e32 v0, s64
	s_mov_b32 s2, 0x5180000
	v_writelane_b32 v255, s0, 30
	s_cselect_b32 s2, s2, 0x9380000
	s_and_b64 s[0:1], s[44:45], exec
	s_mov_b32 s0, 0xd580000
	s_cselect_b32 s3, s0, 0x11780000
	s_and_b64 s[0:1], s[4:5], exec
	v_rcp_iflag_f32_e32 v0, v0
	v_writelane_b32 v255, s58, 32
	s_cselect_b32 s0, 0x19b0000, s3
	v_writelane_b32 v255, s0, 33
	s_and_b64 s[0:1], s[34:35], exec
	s_cselect_b32 s34, 0xd580000, s2
	s_add_u32 s0, s12, 0x19160000
	s_addc_u32 s1, s13, 0
	v_mul_f32_e32 v0, 0x4f7ffffe, v0
	v_writelane_b32 v255, s0, 34
	v_cvt_u32_f32_e32 v0, v0
	s_waitcnt vmcnt(6)
	s_mov_b32 s97, 0
	v_writelane_b32 v255, s1, 35
	s_add_u32 s0, s12, 0x18460000
	s_addc_u32 s1, s13, 0
	v_writelane_b32 v255, s0, 36
	s_mov_b32 s23, s53
	v_add_u32_e32 v187, 0, v2
	v_writelane_b32 v255, s1, 37
	s_sub_i32 s0, 0, s64
	v_readfirstlane_b32 s1, v0
	s_mul_i32 s0, s0, s1
	s_mul_hi_u32 s0, s1, s0
	s_add_i32 s0, s1, s0
	v_writelane_b32 v255, s0, 38
	s_add_u32 s0, s24, 0x80
	v_add_u32_e32 v0, v14, v12
	s_addc_u32 s1, 0, 0
	v_add_lshl_u32 v98, v0, v13, 1
	v_add_u32_e32 v0, v17, v15
	v_lshl_add_u64 v[162:163], s[0:1], 0, v[98:99]
	v_add_lshl_u32 v98, v0, v16, 1
	v_lshl_add_u64 v[164:165], s[0:1], 0, v[98:99]
	s_barrier
	s_waitcnt vmcnt(0)
	s_branch .LBB0_422

.LBB0_432:
	s_add_u32 s16, s42, 0x100
	s_addc_u32 s17, s43, 0
	s_mov_b32 s4, 0
	s_add_u32 s0, s6, s73
	s_addc_u32 s1, s7, 0
	s_add_i32 s42, s4, 2
	s_add_i32 s43, 0, 0x10000
	s_cmp_eq_u32 s21, s4
	s_cselect_b32 s5, s39, s1
	s_cselect_b32 s4, s38, s0
	v_add_u32_e32 v98, s43, v186
	s_cselect_b32 s45, s41, s17
	s_cselect_b32 s44, s40, s16
	s_add_i32 s46, 0, 0x14000
	ds_read_b128 v[132:135], v98
	ds_read_b128 v[136:139], v98 offset:1024
	ds_read_b128 v[140:143], v98 offset:2048
	ds_read_b128 v[144:147], v98 offset:3072
	v_add_u32_e32 v98, s46, v186
	ds_read_b128 v[148:151], v98
	ds_read_b128 v[152:155], v98 offset:1024
	ds_read_b128 v[166:169], v98 offset:2048
	ds_read_b128 v[170:173], v98 offset:3072
	v_lshl_add_u64 v[204:205], s[6:7], 0, v[162:163]
	s_add_i32 m0, s11, 0xc000
	ds_read_b128 v[174:177], v187
	ds_read_b128 v[178:181], v187 offset:1024
	ds_read_b128 v[182:185], v187 offset:2048
	ds_read_b128 v[188:191], v187 offset:3072
	ds_read_b128 v[196:199], v187 offset:4096
	ds_read_b128 v[200:203], v187 offset:5120
	ds_read_b128 v[224:227], v187 offset:6144
	ds_read_b128 v[228:231], v187 offset:7168
	global_load_lds_dwordx4 v[204:205], off
	v_lshl_add_u64 v[204:205], s[6:7], 0, v[164:165]
	s_add_i32 m0, s11, 0xe000
	s_nop 0
	global_load_lds_dwordx4 v[204:205], off
	s_cmp_eq_u32 s93, 2
	s_cbranch_scc1 .Lpw1_up
	s_waitcnt vmcnt(56)
	s_branch .Lpw1_done
.Lpw1_up:
	s_waitcnt vmcnt(24)
.Lpw1_done:
	s_waitcnt lgkmcnt(0)
	s_barrier
	s_setprio 1
	s_waitcnt lgkmcnt(0)
	v_mfma_f32_16x16x32_bf16 v[128:131], v[132:135], v[174:177], 0
	v_mfma_f32_16x16x32_bf16 v[124:127], v[140:143], v[174:177], 0
	v_mfma_f32_16x16x32_bf16 v[112:115], v[132:135], v[182:185], 0
	v_mfma_f32_16x16x32_bf16 v[108:111], v[140:143], v[182:185], 0
	v_mfma_f32_16x16x32_bf16 v[92:95], v[132:135], v[196:199], 0
	v_mfma_f32_16x16x32_bf16 v[88:91], v[140:143], v[196:199], 0
	v_mfma_f32_16x16x32_bf16 v[76:79], v[132:135], v[224:227], 0
	v_mfma_f32_16x16x32_bf16 v[72:75], v[140:143], v[224:227], 0
	v_mfma_f32_16x16x32_bf16 v[128:131], v[136:139], v[178:181], v[128:131]
	v_mfma_f32_16x16x32_bf16 v[124:127], v[144:147], v[178:181], v[124:127]
	v_mfma_f32_16x16x32_bf16 v[112:115], v[136:139], v[188:191], v[112:115]
	v_mfma_f32_16x16x32_bf16 v[108:111], v[144:147], v[188:191], v[108:111]
	v_mfma_f32_16x16x32_bf16 v[92:95], v[136:139], v[200:203], v[92:95]
	v_mfma_f32_16x16x32_bf16 v[88:91], v[144:147], v[200:203], v[88:91]
	v_mfma_f32_16x16x32_bf16 v[76:79], v[136:139], v[228:231], v[76:79]
	v_mfma_f32_16x16x32_bf16 v[72:75], v[144:147], v[228:231], v[72:75]
	s_setprio 0
	s_setprio 1
	v_mfma_f32_16x16x32_bf16 v[120:123], v[148:151], v[174:177], 0
	v_mfma_f32_16x16x32_bf16 v[116:119], v[166:169], v[174:177], 0
	v_mfma_f32_16x16x32_bf16 v[104:107], v[148:151], v[182:185], 0
	v_mfma_f32_16x16x32_bf16 v[100:103], v[166:169], v[182:185], 0
	v_mfma_f32_16x16x32_bf16 v[84:87], v[148:151], v[196:199], 0
	v_mfma_f32_16x16x32_bf16 v[80:83], v[166:169], v[196:199], 0
	v_mfma_f32_16x16x32_bf16 v[68:71], v[148:151], v[224:227], 0
	v_mfma_f32_16x16x32_bf16 v[64:67], v[166:169], v[224:227], 0
	v_mfma_f32_16x16x32_bf16 v[120:123], v[152:155], v[178:181], v[120:123]
	v_mfma_f32_16x16x32_bf16 v[116:119], v[170:173], v[178:181], v[116:119]
	v_mfma_f32_16x16x32_bf16 v[104:107], v[152:155], v[188:191], v[104:107]
	v_mfma_f32_16x16x32_bf16 v[100:103], v[170:173], v[188:191], v[100:103]
	v_mfma_f32_16x16x32_bf16 v[84:87], v[152:155], v[200:203], v[84:87]
	v_mfma_f32_16x16x32_bf16 v[80:83], v[170:173], v[200:203], v[80:83]
	v_mfma_f32_16x16x32_bf16 v[68:71], v[152:155], v[228:231], v[68:71]
	v_mfma_f32_16x16x32_bf16 v[64:67], v[170:173], v[228:231], v[64:67]
	s_setprio 0
	s_barrier
	s_add_i32 s6, s43, s10
	v_lshl_add_u64 v[204:205], s[44:45], 0, v[156:157]
	s_mov_b32 m0, s6
	ds_read_b128 v[174:177], v187 offset:16384
	ds_read_b128 v[178:181], v187 offset:17408
	ds_read_b128 v[182:185], v187 offset:18432
	ds_read_b128 v[188:191], v187 offset:19456
	ds_read_b128 v[196:199], v187 offset:20480
	ds_read_b128 v[200:203], v187 offset:21504
	ds_read_b128 v[224:227], v187 offset:22528
	ds_read_b128 v[228:231], v187 offset:23552
	global_load_lds_dwordx4 v[204:205], off
	s_add_i32 m0, s6, 0x2000
	s_add_u32 s6, s44, s96
	v_lshl_add_u64 v[232:233], s[44:45], 0, v[160:161]
	s_addc_u32 s7, s45, 0
	s_add_i32 s43, s46, s10
	global_load_lds_dwordx4 v[232:233], off
	v_lshl_add_u64 v[234:235], s[6:7], 0, v[156:157]
	s_mov_b32 m0, s43
	v_lshl_add_u64 v[236:237], s[6:7], 0, v[160:161]
	global_load_lds_dwordx4 v[234:235], off
	s_add_i32 m0, s43, 0x2000
	v_lshl_add_u64 v[238:239], s[4:5], 0, v[96:97]
	global_load_lds_dwordx4 v[236:237], off
	s_mov_b32 m0, s11
	v_lshl_add_u64 v[240:241], s[4:5], 0, v[158:159]
	global_load_lds_dwordx4 v[238:239], off
	s_mov_b32 m0, s36
	s_nop 0
	global_load_lds_dwordx4 v[240:241], off
	s_cmp_eq_u32 s93, 2
	s_cbranch_scc1 .Lpw2_up
	s_waitcnt vmcnt(56)
	s_branch .Lpw2_done

.Lpw2_done:
	s_waitcnt lgkmcnt(0)
	s_barrier
	s_setprio 1
	s_waitcnt lgkmcnt(0)
	v_mfma_f32_16x16x32_bf16 v[60:63], v[132:135], v[174:177], 0
	v_mfma_f32_16x16x32_bf16 v[56:59], v[140:143], v[174:177], 0
	v_mfma_f32_16x16x32_bf16 v[44:47], v[132:135], v[182:185], 0
	v_mfma_f32_16x16x32_bf16 v[40:43], v[140:143], v[182:185], 0
	v_mfma_f32_16x16x32_bf16 v[28:31], v[132:135], v[196:199], 0
	v_mfma_f32_16x16x32_bf16 v[24:27], v[140:143], v[196:199], 0
	v_mfma_f32_16x16x32_bf16 v[12:15], v[132:135], v[224:227], 0
	v_mfma_f32_16x16x32_bf16 v[8:11], v[140:143], v[224:227], 0
	v_mfma_f32_16x16x32_bf16 v[60:63], v[136:139], v[178:181], v[60:63]
	v_mfma_f32_16x16x32_bf16 v[56:59], v[144:147], v[178:181], v[56:59]
	v_mfma_f32_16x16x32_bf16 v[44:47], v[136:139], v[188:191], v[44:47]
	v_mfma_f32_16x16x32_bf16 v[40:43], v[144:147], v[188:191], v[40:43]
	v_mfma_f32_16x16x32_bf16 v[28:31], v[136:139], v[200:203], v[28:31]
	v_mfma_f32_16x16x32_bf16 v[24:27], v[144:147], v[200:203], v[24:27]
	v_mfma_f32_16x16x32_bf16 v[12:15], v[136:139], v[228:231], v[12:15]
	v_mfma_f32_16x16x32_bf16 v[8:11], v[144:147], v[228:231], v[8:11]
	s_setprio 0
	s_setprio 1
	v_mfma_f32_16x16x32_bf16 v[52:55], v[148:151], v[174:177], 0
	v_mfma_f32_16x16x32_bf16 v[48:51], v[166:169], v[174:177], 0
	v_mfma_f32_16x16x32_bf16 v[36:39], v[148:151], v[182:185], 0
	v_mfma_f32_16x16x32_bf16 v[32:35], v[166:169], v[182:185], 0
	v_mfma_f32_16x16x32_bf16 v[20:23], v[148:151], v[196:199], 0
	v_mfma_f32_16x16x32_bf16 v[16:19], v[166:169], v[196:199], 0
	v_mfma_f32_16x16x32_bf16 v[4:7], v[148:151], v[224:227], 0
	v_mfma_f32_16x16x32_bf16 v[0:3], v[166:169], v[224:227], 0
	v_mfma_f32_16x16x32_bf16 v[52:55], v[152:155], v[178:181], v[52:55]
	v_mfma_f32_16x16x32_bf16 v[48:51], v[170:173], v[178:181], v[48:51]
	v_mfma_f32_16x16x32_bf16 v[36:39], v[152:155], v[188:191], v[36:39]
	v_mfma_f32_16x16x32_bf16 v[32:35], v[170:173], v[188:191], v[32:35]
	v_mfma_f32_16x16x32_bf16 v[20:23], v[152:155], v[200:203], v[20:23]
	v_mfma_f32_16x16x32_bf16 v[16:19], v[170:173], v[200:203], v[16:19]
	v_mfma_f32_16x16x32_bf16 v[4:7], v[152:155], v[228:231], v[4:7]
	v_mfma_f32_16x16x32_bf16 v[0:3], v[170:173], v[228:231], v[0:3]
	s_setprio 0
	s_barrier
	s_add_i32 s6, 0, 0x18000
	v_add_u32_e32 v98, s6, v186
	s_add_i32 s7, 0, 0x1c000
	ds_read_b128 v[132:135], v98
	ds_read_b128 v[136:139], v98 offset:1024
	ds_read_b128 v[140:143], v98 offset:2048
	ds_read_b128 v[144:147], v98 offset:3072
	v_add_u32_e32 v98, s7, v186
	ds_read_b128 v[148:151], v98
	ds_read_b128 v[152:155], v98 offset:1024
	ds_read_b128 v[166:169], v98 offset:2048
	ds_read_b128 v[170:173], v98 offset:3072
	s_add_u32 s4, s4, s24
	s_addc_u32 s5, s5, 0
	s_mov_b32 m0, s37
	v_lshl_add_u64 v[242:243], s[4:5], 0, v[96:97]
	ds_read_b128 v[174:177], v187 offset:32768
	ds_read_b128 v[178:181], v187 offset:33792
	ds_read_b128 v[182:185], v187 offset:34816
	ds_read_b128 v[188:191], v187 offset:35840
	ds_read_b128 v[196:199], v187 offset:36864
	ds_read_b128 v[200:203], v187 offset:37888
	ds_read_b128 v[224:227], v187 offset:38912
	ds_read_b128 v[228:231], v187 offset:39936
	global_load_lds_dwordx4 v[242:243], off
	v_lshl_add_u64 v[242:243], s[4:5], 0, v[158:159]
	s_mov_b32 m0, s30
	s_nop 0
	global_load_lds_dwordx4 v[242:243], off
	s_waitcnt vmcnt(8)
	s_waitcnt lgkmcnt(0)
	s_barrier
	s_setprio 1
	s_waitcnt lgkmcnt(0)
	v_mfma_f32_16x16x32_bf16 v[128:131], v[132:135], v[174:177], v[128:131]
	v_mfma_f32_16x16x32_bf16 v[124:127], v[140:143], v[174:177], v[124:127]
	v_mfma_f32_16x16x32_bf16 v[112:115], v[132:135], v[182:185], v[112:115]
	v_mfma_f32_16x16x32_bf16 v[108:111], v[140:143], v[182:185], v[108:111]
	v_mfma_f32_16x16x32_bf16 v[92:95], v[132:135], v[196:199], v[92:95]
	v_mfma_f32_16x16x32_bf16 v[88:91], v[140:143], v[196:199], v[88:91]
	v_mfma_f32_16x16x32_bf16 v[76:79], v[132:135], v[224:227], v[76:79]
	v_mfma_f32_16x16x32_bf16 v[72:75], v[140:143], v[224:227], v[72:75]
	v_mfma_f32_16x16x32_bf16 v[128:131], v[136:139], v[178:181], v[128:131]
	v_mfma_f32_16x16x32_bf16 v[124:127], v[144:147], v[178:181], v[124:127]
	v_mfma_f32_16x16x32_bf16 v[112:115], v[136:139], v[188:191], v[112:115]
	v_mfma_f32_16x16x32_bf16 v[108:111], v[144:147], v[188:191], v[108:111]
	v_mfma_f32_16x16x32_bf16 v[92:95], v[136:139], v[200:203], v[92:95]
	v_mfma_f32_16x16x32_bf16 v[88:91], v[144:147], v[200:203], v[88:91]
	v_mfma_f32_16x16x32_bf16 v[76:79], v[136:139], v[228:231], v[76:79]
	v_mfma_f32_16x16x32_bf16 v[72:75], v[144:147], v[228:231], v[72:75]
	s_setprio 0
	s_setprio 1
	v_mfma_f32_16x16x32_bf16 v[120:123], v[148:151], v[174:177], v[120:123]
	v_mfma_f32_16x16x32_bf16 v[116:119], v[166:169], v[174:177], v[116:119]
	v_mfma_f32_16x16x32_bf16 v[104:107], v[148:151], v[182:185], v[104:107]
	v_mfma_f32_16x16x32_bf16 v[100:103], v[166:169], v[182:185], v[100:103]
	v_mfma_f32_16x16x32_bf16 v[84:87], v[148:151], v[196:199], v[84:87]
	v_mfma_f32_16x16x32_bf16 v[80:83], v[166:169], v[196:199], v[80:83]
	v_mfma_f32_16x16x32_bf16 v[68:71], v[148:151], v[224:227], v[68:71]
	v_mfma_f32_16x16x32_bf16 v[64:67], v[166:169], v[224:227], v[64:67]
	v_mfma_f32_16x16x32_bf16 v[120:123], v[152:155], v[178:181], v[120:123]
	v_mfma_f32_16x16x32_bf16 v[116:119], v[170:173], v[178:181], v[116:119]
	v_mfma_f32_16x16x32_bf16 v[104:107], v[152:155], v[188:191], v[104:107]
	v_mfma_f32_16x16x32_bf16 v[100:103], v[170:173], v[188:191], v[100:103]
	v_mfma_f32_16x16x32_bf16 v[84:87], v[152:155], v[200:203], v[84:87]
	v_mfma_f32_16x16x32_bf16 v[80:83], v[170:173], v[200:203], v[80:83]
	v_mfma_f32_16x16x32_bf16 v[68:71], v[152:155], v[228:231], v[68:71]
	v_mfma_f32_16x16x32_bf16 v[64:67], v[170:173], v[228:231], v[64:67]
	s_setprio 0
	s_barrier
	s_add_i32 s4, s6, s10
	v_lshl_add_u64 v[204:205], v[204:205], 0, s[60:61]
	s_mov_b32 m0, s4
	ds_read_b128 v[174:177], v187 offset:49152
	ds_read_b128 v[178:181], v187 offset:50176
	ds_read_b128 v[182:185], v187 offset:51200
	ds_read_b128 v[188:191], v187 offset:52224
	ds_read_b128 v[196:199], v187 offset:53248
	ds_read_b128 v[200:203], v187 offset:54272
	ds_read_b128 v[224:227], v187 offset:55296
	ds_read_b128 v[228:231], v187 offset:56320
	global_load_lds_dwordx4 v[204:205], off
	v_lshl_add_u64 v[204:205], v[232:233], 0, s[60:61]
	s_add_i32 m0, s4, 0x2000
	s_add_i32 s4, s7, s10
	global_load_lds_dwordx4 v[204:205], off
	v_lshl_add_u64 v[204:205], v[234:235], 0, s[60:61]
	s_mov_b32 m0, s4
	s_nop 0
	global_load_lds_dwordx4 v[204:205], off
	v_lshl_add_u64 v[204:205], v[236:237], 0, s[60:61]
	s_add_i32 m0, s4, 0x2000
	s_nop 0
	global_load_lds_dwordx4 v[204:205], off
	v_lshl_add_u64 v[204:205], v[238:239], 0, s[60:61]
	s_mov_b32 m0, s31
	s_nop 0
	global_load_lds_dwordx4 v[204:205], off
	v_lshl_add_u64 v[204:205], v[240:241], 0, s[60:61]
	s_mov_b32 m0, s18
	s_nop 0
	global_load_lds_dwordx4 v[204:205], off
	s_waitcnt vmcnt(8)
	s_waitcnt lgkmcnt(0)
	s_barrier
	s_setprio 1
	s_waitcnt lgkmcnt(0)
	v_mfma_f32_16x16x32_bf16 v[60:63], v[132:135], v[174:177], v[60:63]
	v_mfma_f32_16x16x32_bf16 v[56:59], v[140:143], v[174:177], v[56:59]
	v_mfma_f32_16x16x32_bf16 v[44:47], v[132:135], v[182:185], v[44:47]
	v_mfma_f32_16x16x32_bf16 v[40:43], v[140:143], v[182:185], v[40:43]
	v_mfma_f32_16x16x32_bf16 v[28:31], v[132:135], v[196:199], v[28:31]
	v_mfma_f32_16x16x32_bf16 v[24:27], v[140:143], v[196:199], v[24:27]
	v_mfma_f32_16x16x32_bf16 v[12:15], v[132:135], v[224:227], v[12:15]
	v_mfma_f32_16x16x32_bf16 v[8:11], v[140:143], v[224:227], v[8:11]
	v_mfma_f32_16x16x32_bf16 v[60:63], v[136:139], v[178:181], v[60:63]
	v_mfma_f32_16x16x32_bf16 v[56:59], v[144:147], v[178:181], v[56:59]
	v_mfma_f32_16x16x32_bf16 v[44:47], v[136:139], v[188:191], v[44:47]
	v_mfma_f32_16x16x32_bf16 v[40:43], v[144:147], v[188:191], v[40:43]
	v_mfma_f32_16x16x32_bf16 v[28:31], v[136:139], v[200:203], v[28:31]
	v_mfma_f32_16x16x32_bf16 v[24:27], v[144:147], v[200:203], v[24:27]
	v_mfma_f32_16x16x32_bf16 v[12:15], v[136:139], v[228:231], v[12:15]
	v_mfma_f32_16x16x32_bf16 v[8:11], v[144:147], v[228:231], v[8:11]
	s_setprio 0
	s_setprio 1
	v_mfma_f32_16x16x32_bf16 v[52:55], v[148:151], v[174:177], v[52:55]
	v_mfma_f32_16x16x32_bf16 v[48:51], v[166:169], v[174:177], v[48:51]
	v_mfma_f32_16x16x32_bf16 v[36:39], v[148:151], v[182:185], v[36:39]
	v_mfma_f32_16x16x32_bf16 v[32:35], v[166:169], v[182:185], v[32:35]
	v_mfma_f32_16x16x32_bf16 v[20:23], v[148:151], v[196:199], v[20:23]
	v_mfma_f32_16x16x32_bf16 v[16:19], v[166:169], v[196:199], v[16:19]
	v_mfma_f32_16x16x32_bf16 v[4:7], v[148:151], v[224:227], v[4:7]
	v_mfma_f32_16x16x32_bf16 v[0:3], v[166:169], v[224:227], v[0:3]
	v_mfma_f32_16x16x32_bf16 v[52:55], v[152:155], v[178:181], v[52:55]
	v_mfma_f32_16x16x32_bf16 v[48:51], v[170:173], v[178:181], v[48:51]
	v_mfma_f32_16x16x32_bf16 v[36:39], v[152:155], v[188:191], v[36:39]
	v_mfma_f32_16x16x32_bf16 v[32:35], v[170:173], v[188:191], v[32:35]
	v_mfma_f32_16x16x32_bf16 v[20:23], v[152:155], v[200:203], v[20:23]
	v_mfma_f32_16x16x32_bf16 v[16:19], v[170:173], v[200:203], v[16:19]
	v_mfma_f32_16x16x32_bf16 v[4:7], v[152:155], v[228:231], v[4:7]
	v_mfma_f32_16x16x32_bf16 v[0:3], v[170:173], v[228:231], v[0:3]
	s_setprio 0
	s_barrier
	s_add_u32 s16, s16, 0x100
	s_addc_u32 s17, s17, 0
	s_cmp_ge_u32 s42, s88
	s_mov_b64 s[6:7], s[0:1]
	s_mov_b32 s4, s42
	s_cbranch_scc1 .Lkl_exit

.Lkl_exit:
	s_and_b64 vcc, exec, s[28:29]
	s_cbranch_vccz .LBB0_436
	s_barrier

.LBB0_892:
	v_or_b32_e32 v98, s19, v182
	v_ashrrev_i32_e32 v169, 31, v168
	s_lshl_b32 s0, s90, 8
	v_lshlrev_b64 v[200:201], 1, v[168:169]
	v_lshl_add_u32 v170, s67, 8, v98
	s_ashr_i32 s1, s0, 31
	v_lshl_add_u64 v[132:133], s[44:45], 0, v[200:201]
	s_lshl_b64 s[6:7], s[0:1], 1
	v_ashrrev_i32_e32 v171, 31, v170
	v_or_b32_e32 v180, 16, v170
	v_lshl_add_u64 v[172:173], v[132:133], 0, s[6:7]
	v_lshlrev_b64 v[202:203], 11, v[170:171]
	v_ashrrev_i32_e32 v181, 31, v180
	v_or_b32_e32 v176, 32, v170
	v_lshl_add_u64 v[132:133], v[172:173], 0, v[202:203]
	v_lshlrev_b64 v[184:185], 11, v[180:181]
	v_ashrrev_i32_e32 v177, 31, v176
	v_or_b32_e32 v174, 48, v170
	global_load_dwordx4 v[188:191], v[132:133], off
	global_load_dwordx4 v[196:199], v[132:133], off offset:256
	v_lshl_add_u64 v[132:133], v[172:173], 0, v[184:185]
	v_lshlrev_b64 v[182:183], 11, v[176:177]
	v_ashrrev_i32_e32 v175, 31, v174
	global_load_dwordx4 v[152:155], v[132:133], off
	global_load_dwordx4 v[148:151], v[132:133], off offset:256
	v_lshl_add_u64 v[132:133], v[172:173], 0, v[182:183]
	v_lshlrev_b64 v[178:179], 11, v[174:175]
	global_load_dwordx4 v[144:147], v[132:133], off
	global_load_dwordx4 v[140:143], v[132:133], off offset:256
	v_lshl_add_u64 v[132:133], v[172:173], 0, v[178:179]
	global_load_dwordx4 v[136:139], v[132:133], off
	s_nop 0
	global_load_dwordx4 v[132:135], v[132:133], off offset:256
	v_lshl_add_u64 v[202:203], s[44:45], 0, v[202:203]
	v_lshl_add_u64 v[202:203], v[202:203], 0, s[6:7]
	v_lshl_add_u64 v[200:201], v[202:203], 0, v[200:201]
	v_cmp_gt_i32_e64 s[4:5], 2, v166
	v_cmp_gt_u32_e32 vcc, 16, v167
	v_ashrrev_i32_e32 v167, 31, v166
	s_waitcnt vmcnt(0)
	s_nop 0
	v_lshlrev_b32_e32 v202, 16, v188
	v_and_b32_e32 v203, 0xffff0000, v188
	v_lshlrev_b32_e32 v188, 16, v189
	v_and_b32_e32 v189, 0xffff0000, v189
	v_lshlrev_b32_e32 v204, 16, v190
	v_and_b32_e32 v205, 0xffff0000, v190
	v_lshlrev_b32_e32 v190, 16, v191
	v_and_b32_e32 v191, 0xffff0000, v191
	v_pk_add_f32 v[130:131], v[130:131], v[188:189]
	v_pk_add_f32 v[128:129], v[128:129], v[202:203]
	v_pk_add_f32 v[188:189], v[126:127], v[190:191]
	v_pk_add_f32 v[126:127], v[124:125], v[204:205]
	v_mul_f32_e32 v98, v129, v129
	v_mul_f32_e32 v124, v131, v131
	v_fmac_f32_e32 v98, v128, v128
	v_fmac_f32_e32 v124, v130, v130
	v_add_f32_e32 v98, v98, v124
	v_mul_f32_e32 v124, v127, v127
	v_fmac_f32_e32 v124, v126, v126
	v_add_f32_e32 v98, v124, v98
	v_mul_f32_e32 v124, v189, v189
	v_fmac_f32_e32 v124, v188, v188
	v_add_f32_e32 v98, v124, v98
	v_cvt_pk_bf16_f32 v124, v128, v129
	v_cvt_pk_bf16_f32 v125, v130, v131
	v_cvt_pk_bf16_f32 v126, v126, v127
	v_cvt_pk_bf16_f32 v127, v188, v189
	global_store_dwordx4 v[200:201], v[124:127], off
	v_lshlrev_b32_e32 v128, 16, v198
	v_and_b32_e32 v129, 0xffff0000, v198
	v_lshlrev_b32_e32 v124, 16, v196
	v_and_b32_e32 v125, 0xffff0000, v196
	v_lshlrev_b32_e32 v126, 16, v197
	v_and_b32_e32 v127, 0xffff0000, v197
	v_lshlrev_b32_e32 v130, 16, v199
	v_and_b32_e32 v131, 0xffff0000, v199
	v_pk_add_f32 v[122:123], v[122:123], v[126:127]
	v_pk_add_f32 v[120:121], v[120:121], v[124:125]
	v_pk_add_f32 v[124:125], v[118:119], v[130:131]
	v_pk_add_f32 v[118:119], v[116:117], v[128:129]
	v_mul_f32_e32 v116, v121, v121
	v_mul_f32_e32 v117, v123, v123
	v_fmac_f32_e32 v116, v120, v120
	v_fmac_f32_e32 v117, v122, v122
	v_add_f32_e32 v116, v116, v117
	v_mul_f32_e32 v117, v119, v119
	v_fmac_f32_e32 v117, v118, v118
	v_add_f32_e32 v116, v117, v116
	v_mul_f32_e32 v117, v125, v125
	v_fmac_f32_e32 v117, v124, v124
	v_add_f32_e32 v116, v117, v116
	v_add_f32_e32 v126, v98, v116
	v_cvt_pk_bf16_f32 v116, v120, v121
	v_cvt_pk_bf16_f32 v117, v122, v123
	v_cvt_pk_bf16_f32 v118, v118, v119
	v_cvt_pk_bf16_f32 v119, v124, v125
	global_store_dwordx4 v[200:201], v[116:119], off offset:256
	v_xor_b32_e32 v98, 16, v214
	s_nop 0
	v_and_b32_e32 v116, 64, v214
	v_add_u32_e32 v116, 64, v116
	v_cmp_lt_i32_e64 s[6:7], v98, v116
	v_xor_b32_e32 v118, 32, v214
	s_nop 0
	v_cndmask_b32_e64 v98, v214, v98, s[6:7]
	v_lshlrev_b32_e32 v98, 2, v98
	ds_bpermute_b32 v117, v98, v126
	v_cmp_lt_i32_e64 s[6:7], v118, v116
	s_waitcnt lgkmcnt(0)
	v_add_f32_e32 v117, v126, v117
	v_cndmask_b32_e64 v116, v214, v118, s[6:7]
	v_lshlrev_b32_e32 v116, 2, v116
	ds_bpermute_b32 v118, v116, v117
	s_and_saveexec_b64 s[6:7], s[4:5]
	s_cbranch_execz .LBB0_894
	s_waitcnt lgkmcnt(0)
	v_add_f32_e32 v117, v117, v118
	s_lshl_b32 s16, s90, 3
	v_lshlrev_b64 v[118:119], 7, v[170:171]
	s_ashr_i32 s17, s16, 31
	v_lshl_add_u64 v[118:119], s[42:43], 0, v[118:119]
	v_lshl_add_u64 v[118:119], s[16:17], 2, v[118:119]
	s_lshl_b32 s52, s91, 2
	v_lshl_add_u64 v[118:119], v[118:119], 0, s[52:53]
	v_cndmask_b32_e32 v117, 0, v117, vcc
	v_lshl_add_u64 v[118:119], v[166:167], 2, v[118:119]
	global_store_dword v[118:119], v117, off
.LBB0_894:
	s_or_b64 exec, exec, s[6:7]
	v_lshlrev_b32_e32 v120, 16, v152
	v_and_b32_e32 v121, 0xffff0000, v152
	v_lshlrev_b32_e32 v122, 16, v153
	v_and_b32_e32 v123, 0xffff0000, v153
	v_lshlrev_b32_e32 v124, 16, v154
	v_and_b32_e32 v125, 0xffff0000, v154
	v_lshlrev_b32_e32 v126, 16, v155
	v_and_b32_e32 v127, 0xffff0000, v155
	v_pk_add_f32 v[114:115], v[114:115], v[122:123]
	v_pk_add_f32 v[112:113], v[112:113], v[120:121]
	v_pk_add_f32 v[120:121], v[110:111], v[126:127]
	v_pk_add_f32 v[110:111], v[108:109], v[124:125]
	v_mul_f32_e32 v108, v113, v113
	v_mul_f32_e32 v109, v115, v115
	v_fmac_f32_e32 v108, v112, v112
	v_fmac_f32_e32 v109, v114, v114
	v_add_f32_e32 v108, v108, v109
	v_mul_f32_e32 v109, v111, v111
	v_fmac_f32_e32 v109, v110, v110
	v_add_f32_e32 v108, v109, v108
	v_mul_f32_e32 v109, v121, v121
	v_fmac_f32_e32 v109, v120, v120
	v_add_f32_e32 v117, v109, v108
	v_cvt_pk_bf16_f32 v108, v112, v113
	v_cvt_pk_bf16_f32 v109, v114, v115
	v_lshlrev_b32_e32 v112, 16, v148
	v_and_b32_e32 v113, 0xffff0000, v148
	v_lshlrev_b32_e32 v114, 16, v149
	v_and_b32_e32 v115, 0xffff0000, v149
	v_lshlrev_b32_e32 v122, 16, v150
	v_and_b32_e32 v123, 0xffff0000, v150
	v_pk_add_f32 v[106:107], v[106:107], v[114:115]
	v_pk_add_f32 v[104:105], v[104:105], v[112:113]
	v_pk_add_f32 v[114:115], v[100:101], v[122:123]
	v_mul_f32_e32 v100, v105, v105
	v_mul_f32_e32 v101, v107, v107
	v_fmac_f32_e32 v100, v104, v104
	v_fmac_f32_e32 v101, v106, v106
	v_lshlrev_b32_e32 v124, 16, v151
	v_and_b32_e32 v125, 0xffff0000, v151
	v_add_f32_e32 v100, v100, v101
	v_mul_f32_e32 v101, v115, v115
	v_pk_add_f32 v[112:113], v[102:103], v[124:125]
	v_fmac_f32_e32 v101, v114, v114
	v_add_f32_e32 v100, v101, v100
	v_mul_f32_e32 v101, v113, v113
	v_fmac_f32_e32 v101, v112, v112
	v_add_f32_e32 v100, v101, v100
	v_add_f32_e32 v100, v117, v100
	ds_bpermute_b32 v101, v98, v100
	s_waitcnt lgkmcnt(0)
	v_lshl_add_u64 v[118:119], s[44:45], 0, v[184:185]
	v_lshl_add_u64 v[118:119], s[0:1], 1, v[118:119]
	v_lshl_add_u64 v[118:119], v[168:169], 1, v[118:119]
	v_cvt_pk_bf16_f32 v110, v110, v111
	v_add_f32_e32 v100, v100, v101
	ds_bpermute_b32 v101, v116, v100
	v_cvt_pk_bf16_f32 v111, v120, v121
	global_store_dwordx4 v[118:119], v[108:111], off
	v_cvt_pk_bf16_f32 v102, v104, v105
	v_cvt_pk_bf16_f32 v103, v106, v107
	v_cvt_pk_bf16_f32 v104, v114, v115
	v_cvt_pk_bf16_f32 v105, v112, v113
	global_store_dwordx4 v[118:119], v[102:105], off offset:256
	s_and_saveexec_b64 s[6:7], s[4:5]
	s_cbranch_execz .LBB0_896
	s_waitcnt lgkmcnt(0)
	v_add_f32_e32 v100, v100, v101
	v_cndmask_b32_e32 v102, 0, v100, vcc
	s_lshl_b32 s16, s90, 3
	v_lshlrev_b64 v[100:101], 7, v[180:181]
	s_ashr_i32 s17, s16, 31
	v_lshl_add_u64 v[100:101], s[42:43], 0, v[100:101]
	v_lshl_add_u64 v[100:101], s[16:17], 2, v[100:101]
	s_lshl_b32 s52, s91, 2
	v_lshl_add_u64 v[100:101], v[100:101], 0, s[52:53]
	v_lshl_add_u64 v[100:101], v[166:167], 2, v[100:101]
	global_store_dword v[100:101], v102, off
.LBB0_896:
	s_or_b64 exec, exec, s[6:7]
	v_lshlrev_b32_e32 v102, 16, v144
	v_and_b32_e32 v103, 0xffff0000, v144
	v_lshlrev_b32_e32 v104, 16, v145
	v_and_b32_e32 v105, 0xffff0000, v145
	v_lshlrev_b32_e32 v106, 16, v146
	v_and_b32_e32 v107, 0xffff0000, v146
	v_lshlrev_b32_e32 v108, 16, v147
	v_and_b32_e32 v109, 0xffff0000, v147
	v_pk_add_f32 v[94:95], v[94:95], v[104:105]
	v_pk_add_f32 v[92:93], v[92:93], v[102:103]
	v_pk_add_f32 v[102:103], v[90:91], v[108:109]
	v_pk_add_f32 v[90:91], v[88:89], v[106:107]
	v_mul_f32_e32 v88, v93, v93
	v_mul_f32_e32 v89, v95, v95
	v_fmac_f32_e32 v88, v92, v92
	v_fmac_f32_e32 v89, v94, v94
	v_add_f32_e32 v88, v88, v89
	v_mul_f32_e32 v89, v91, v91
	v_fmac_f32_e32 v89, v90, v90
	v_add_f32_e32 v88, v89, v88
	v_mul_f32_e32 v89, v103, v103
	v_fmac_f32_e32 v89, v102, v102
	v_add_f32_e32 v108, v89, v88
	v_cvt_pk_bf16_f32 v88, v92, v93
	v_cvt_pk_bf16_f32 v89, v94, v95
	v_lshlrev_b32_e32 v92, 16, v140
	v_and_b32_e32 v93, 0xffff0000, v140
	v_lshlrev_b32_e32 v94, 16, v141
	v_and_b32_e32 v95, 0xffff0000, v141
	v_lshlrev_b32_e32 v104, 16, v142
	v_and_b32_e32 v105, 0xffff0000, v142
	v_pk_add_f32 v[86:87], v[86:87], v[94:95]
	v_pk_add_f32 v[84:85], v[84:85], v[92:93]
	v_pk_add_f32 v[94:95], v[80:81], v[104:105]
	v_mul_f32_e32 v80, v85, v85
	v_mul_f32_e32 v81, v87, v87
	v_fmac_f32_e32 v80, v84, v84
	v_fmac_f32_e32 v81, v86, v86
	v_lshlrev_b32_e32 v106, 16, v143
	v_and_b32_e32 v107, 0xffff0000, v143
	v_add_f32_e32 v80, v80, v81
	v_mul_f32_e32 v81, v95, v95
	v_pk_add_f32 v[92:93], v[82:83], v[106:107]
	v_fmac_f32_e32 v81, v94, v94
	v_add_f32_e32 v80, v81, v80
	v_mul_f32_e32 v81, v93, v93
	v_fmac_f32_e32 v81, v92, v92
	v_add_f32_e32 v80, v81, v80
	v_add_f32_e32 v80, v108, v80
	ds_bpermute_b32 v81, v98, v80
	s_waitcnt lgkmcnt(0)
	v_lshl_add_u64 v[100:101], s[44:45], 0, v[182:183]
	v_lshl_add_u64 v[100:101], s[0:1], 1, v[100:101]
	v_lshl_add_u64 v[100:101], v[168:169], 1, v[100:101]
	v_cvt_pk_bf16_f32 v90, v90, v91
	v_add_f32_e32 v80, v80, v81
	ds_bpermute_b32 v81, v116, v80
	v_cvt_pk_bf16_f32 v91, v102, v103
	global_store_dwordx4 v[100:101], v[88:91], off
	v_cvt_pk_bf16_f32 v82, v84, v85
	v_cvt_pk_bf16_f32 v83, v86, v87
	v_cvt_pk_bf16_f32 v84, v94, v95
	v_cvt_pk_bf16_f32 v85, v92, v93
	global_store_dwordx4 v[100:101], v[82:85], off offset:256
	s_and_saveexec_b64 s[6:7], s[4:5]
	s_cbranch_execz .LBB0_898
	s_waitcnt lgkmcnt(0)
	v_add_f32_e32 v80, v80, v81
	v_cndmask_b32_e32 v82, 0, v80, vcc
	s_lshl_b32 s16, s90, 3
	v_lshlrev_b64 v[80:81], 7, v[176:177]
	s_ashr_i32 s17, s16, 31
	v_lshl_add_u64 v[80:81], s[42:43], 0, v[80:81]
	v_lshl_add_u64 v[80:81], s[16:17], 2, v[80:81]
	s_lshl_b32 s52, s91, 2
	v_lshl_add_u64 v[80:81], v[80:81], 0, s[52:53]
	v_lshl_add_u64 v[80:81], v[166:167], 2, v[80:81]
	global_store_dword v[80:81], v82, off
.LBB0_898:
	s_or_b64 exec, exec, s[6:7]
	v_lshlrev_b32_e32 v82, 16, v136
	v_and_b32_e32 v83, 0xffff0000, v136
	v_lshlrev_b32_e32 v84, 16, v137
	v_and_b32_e32 v85, 0xffff0000, v137
	v_lshlrev_b32_e32 v86, 16, v138
	v_and_b32_e32 v87, 0xffff0000, v138
	v_lshlrev_b32_e32 v88, 16, v139
	v_and_b32_e32 v89, 0xffff0000, v139
	v_pk_add_f32 v[78:79], v[78:79], v[84:85]
	v_pk_add_f32 v[76:77], v[76:77], v[82:83]
	v_pk_add_f32 v[82:83], v[74:75], v[88:89]
	v_pk_add_f32 v[74:75], v[72:73], v[86:87]
	v_mul_f32_e32 v72, v77, v77
	v_mul_f32_e32 v73, v79, v79
	v_fmac_f32_e32 v72, v76, v76
	v_fmac_f32_e32 v73, v78, v78
	v_add_f32_e32 v72, v72, v73
	v_mul_f32_e32 v73, v75, v75
	v_fmac_f32_e32 v73, v74, v74
	v_add_f32_e32 v72, v73, v72
	v_mul_f32_e32 v73, v83, v83
	v_fmac_f32_e32 v73, v82, v82
	v_add_f32_e32 v88, v73, v72
	v_cvt_pk_bf16_f32 v72, v76, v77
	v_cvt_pk_bf16_f32 v73, v78, v79
	v_lshlrev_b32_e32 v76, 16, v132
	v_and_b32_e32 v77, 0xffff0000, v132
	v_lshlrev_b32_e32 v78, 16, v133
	v_and_b32_e32 v79, 0xffff0000, v133
	v_lshlrev_b32_e32 v84, 16, v134
	v_and_b32_e32 v85, 0xffff0000, v134
	v_pk_add_f32 v[70:71], v[70:71], v[78:79]
	v_pk_add_f32 v[68:69], v[68:69], v[76:77]
	v_pk_add_f32 v[78:79], v[64:65], v[84:85]
	v_mul_f32_e32 v64, v69, v69
	v_mul_f32_e32 v65, v71, v71
	v_fmac_f32_e32 v64, v68, v68
	v_fmac_f32_e32 v65, v70, v70
	v_lshlrev_b32_e32 v86, 16, v135
	v_and_b32_e32 v87, 0xffff0000, v135
	v_add_f32_e32 v64, v64, v65
	v_mul_f32_e32 v65, v79, v79
	v_pk_add_f32 v[76:77], v[66:67], v[86:87]
	v_fmac_f32_e32 v65, v78, v78
	v_add_f32_e32 v64, v65, v64
	v_mul_f32_e32 v65, v77, v77
	v_fmac_f32_e32 v65, v76, v76
	v_add_f32_e32 v64, v65, v64
	v_add_f32_e32 v64, v88, v64
	ds_bpermute_b32 v65, v98, v64
	s_waitcnt lgkmcnt(0)
	v_lshl_add_u64 v[80:81], s[44:45], 0, v[178:179]
	v_lshl_add_u64 v[80:81], s[0:1], 1, v[80:81]
	v_lshl_add_u64 v[80:81], v[168:169], 1, v[80:81]
	v_cvt_pk_bf16_f32 v74, v74, v75
	v_add_f32_e32 v64, v64, v65
	ds_bpermute_b32 v65, v116, v64
	v_cvt_pk_bf16_f32 v75, v82, v83
	global_store_dwordx4 v[80:81], v[72:75], off
	v_cvt_pk_bf16_f32 v66, v68, v69
	v_cvt_pk_bf16_f32 v67, v70, v71
	v_cvt_pk_bf16_f32 v68, v78, v79
	v_cvt_pk_bf16_f32 v69, v76, v77
	global_store_dwordx4 v[80:81], v[66:69], off offset:256
	s_and_saveexec_b64 s[6:7], s[4:5]
	s_cbranch_execz .LBB0_900
	s_waitcnt lgkmcnt(0)
	v_add_f32_e32 v64, v64, v65
	v_cndmask_b32_e32 v66, 0, v64, vcc
	s_lshl_b32 s16, s90, 3
	v_lshlrev_b64 v[64:65], 7, v[174:175]
	s_ashr_i32 s17, s16, 31
	v_lshl_add_u64 v[64:65], s[42:43], 0, v[64:65]
	v_lshl_add_u64 v[64:65], s[16:17], 2, v[64:65]
	s_lshl_b32 s52, s91, 2
	v_lshl_add_u64 v[64:65], v[64:65], 0, s[52:53]
	v_lshl_add_u64 v[64:65], v[166:167], 2, v[64:65]
	global_store_dword v[64:65], v66, off
.LBB0_900:
	s_or_b64 exec, exec, s[6:7]
	v_add_u32_e32 v94, 0x80, v170
	v_ashrrev_i32_e32 v95, 31, v94
	v_add_u32_e32 v92, 0x90, v170
	v_lshlrev_b64 v[102:103], 11, v[94:95]
	v_ashrrev_i32_e32 v93, 31, v92
	s_waitcnt lgkmcnt(0)
	v_lshl_add_u64 v[64:65], v[172:173], 0, v[102:103]
	v_lshlrev_b64 v[100:101], 11, v[92:93]
	v_add_u32_e32 v90, 0xa0, v170
	global_load_dwordx4 v[104:107], v[64:65], off
	global_load_dwordx4 v[108:111], v[64:65], off offset:256
	v_lshl_add_u64 v[64:65], v[172:173], 0, v[100:101]
	v_ashrrev_i32_e32 v91, 31, v90
	global_load_dwordx4 v[84:87], v[64:65], off
	global_load_dwordx4 v[80:83], v[64:65], off offset:256
	v_lshlrev_b64 v[64:65], 11, v[90:91]
	v_add_u32_e32 v88, 0xb0, v170
	v_lshl_add_u64 v[64:65], v[172:173], 0, v[64:65]
	v_ashrrev_i32_e32 v89, 31, v88
	global_load_dwordx4 v[76:79], v[64:65], off
	global_load_dwordx4 v[72:75], v[64:65], off offset:256
	v_lshlrev_b64 v[64:65], 11, v[88:89]
	v_lshl_add_u64 v[64:65], v[172:173], 0, v[64:65]
	global_load_dwordx4 v[68:71], v[64:65], off
	s_nop 0
	global_load_dwordx4 v[64:67], v[64:65], off offset:256
	v_lshl_add_u64 v[102:103], s[44:45], 0, v[102:103]
	v_lshl_add_u64 v[102:103], s[0:1], 1, v[102:103]
	v_lshl_add_u64 v[102:103], v[168:169], 1, v[102:103]
	s_waitcnt vmcnt(0)
	s_nop 0
	v_lshlrev_b32_e32 v112, 16, v104
	v_and_b32_e32 v113, 0xffff0000, v104
	v_lshlrev_b32_e32 v104, 16, v105
	v_and_b32_e32 v105, 0xffff0000, v105
	v_lshlrev_b32_e32 v114, 16, v106
	v_and_b32_e32 v115, 0xffff0000, v106
	v_lshlrev_b32_e32 v106, 16, v107
	v_and_b32_e32 v107, 0xffff0000, v107
	v_pk_add_f32 v[62:63], v[62:63], v[104:105]
	v_pk_add_f32 v[60:61], v[60:61], v[112:113]
	v_pk_add_f32 v[104:105], v[58:59], v[106:107]
	v_pk_add_f32 v[58:59], v[56:57], v[114:115]
	v_mul_f32_e32 v56, v61, v61
	v_mul_f32_e32 v57, v63, v63
	v_fmac_f32_e32 v56, v60, v60
	v_fmac_f32_e32 v57, v62, v62
	v_add_f32_e32 v56, v56, v57
	v_mul_f32_e32 v57, v59, v59
	v_fmac_f32_e32 v57, v58, v58
	v_add_f32_e32 v56, v57, v56
	v_mul_f32_e32 v57, v105, v105
	v_fmac_f32_e32 v57, v104, v104
	v_add_f32_e32 v106, v57, v56
	v_cvt_pk_bf16_f32 v56, v60, v61
	v_cvt_pk_bf16_f32 v57, v62, v63
	v_cvt_pk_bf16_f32 v58, v58, v59
	v_cvt_pk_bf16_f32 v59, v104, v105
	global_store_dwordx4 v[102:103], v[56:59], off
	v_lshlrev_b32_e32 v60, 16, v110
	v_and_b32_e32 v61, 0xffff0000, v110
	v_lshlrev_b32_e32 v56, 16, v108
	v_and_b32_e32 v57, 0xffff0000, v108
	v_lshlrev_b32_e32 v58, 16, v109
	v_and_b32_e32 v59, 0xffff0000, v109
	v_lshlrev_b32_e32 v62, 16, v111
	v_and_b32_e32 v63, 0xffff0000, v111
	v_pk_add_f32 v[54:55], v[54:55], v[58:59]
	v_pk_add_f32 v[52:53], v[52:53], v[56:57]
	v_pk_add_f32 v[56:57], v[50:51], v[62:63]
	v_pk_add_f32 v[50:51], v[48:49], v[60:61]
	v_mul_f32_e32 v48, v53, v53
	v_mul_f32_e32 v49, v55, v55
	v_fmac_f32_e32 v48, v52, v52
	v_fmac_f32_e32 v49, v54, v54
	v_add_f32_e32 v48, v48, v49
	v_mul_f32_e32 v49, v51, v51
	v_fmac_f32_e32 v49, v50, v50
	v_add_f32_e32 v48, v49, v48
	v_mul_f32_e32 v49, v57, v57
	v_fmac_f32_e32 v49, v56, v56
	v_add_f32_e32 v48, v49, v48
	v_add_f32_e32 v58, v106, v48
	v_cvt_pk_bf16_f32 v48, v52, v53
	v_cvt_pk_bf16_f32 v49, v54, v55
	v_cvt_pk_bf16_f32 v50, v50, v51
	v_cvt_pk_bf16_f32 v51, v56, v57
	global_store_dwordx4 v[102:103], v[48:51], off offset:256
	ds_bpermute_b32 v48, v98, v58
	s_waitcnt lgkmcnt(0)
	v_add_f32_e32 v48, v58, v48
	ds_bpermute_b32 v49, v116, v48
	s_and_saveexec_b64 s[6:7], s[4:5]
	s_cbranch_execz .LBB0_902
	s_waitcnt lgkmcnt(0)
	v_add_f32_e32 v48, v48, v49
	v_cndmask_b32_e32 v50, 0, v48, vcc
	s_lshl_b32 s16, s90, 3
	v_lshlrev_b64 v[48:49], 7, v[94:95]
	s_ashr_i32 s17, s16, 31
	v_lshl_add_u64 v[48:49], s[42:43], 0, v[48:49]
	v_lshl_add_u64 v[48:49], s[16:17], 2, v[48:49]
	s_lshl_b32 s52, s91, 2
	v_lshl_add_u64 v[48:49], v[48:49], 0, s[52:53]
	v_lshl_add_u64 v[48:49], v[166:167], 2, v[48:49]
	global_store_dword v[48:49], v50, off
.LBB0_902:
	s_or_b64 exec, exec, s[6:7]
	v_lshlrev_b32_e32 v50, 16, v84
	v_and_b32_e32 v51, 0xffff0000, v84
	v_lshlrev_b32_e32 v52, 16, v85
	v_and_b32_e32 v53, 0xffff0000, v85
	v_lshlrev_b32_e32 v54, 16, v86
	v_and_b32_e32 v55, 0xffff0000, v86
	v_lshlrev_b32_e32 v56, 16, v87
	v_and_b32_e32 v57, 0xffff0000, v87
	v_pk_add_f32 v[46:47], v[46:47], v[52:53]
	v_pk_add_f32 v[44:45], v[44:45], v[50:51]
	v_pk_add_f32 v[50:51], v[42:43], v[56:57]
	v_pk_add_f32 v[42:43], v[40:41], v[54:55]
	v_mul_f32_e32 v40, v45, v45
	v_mul_f32_e32 v41, v47, v47
	v_fmac_f32_e32 v40, v44, v44
	v_fmac_f32_e32 v41, v46, v46
	v_add_f32_e32 v40, v40, v41
	v_mul_f32_e32 v41, v43, v43
	v_fmac_f32_e32 v41, v42, v42
	v_add_f32_e32 v40, v41, v40
	v_mul_f32_e32 v41, v51, v51
	v_fmac_f32_e32 v41, v50, v50
	v_add_f32_e32 v56, v41, v40
	v_cvt_pk_bf16_f32 v40, v44, v45
	v_cvt_pk_bf16_f32 v41, v46, v47
	v_lshlrev_b32_e32 v44, 16, v80
	v_and_b32_e32 v45, 0xffff0000, v80
	v_lshlrev_b32_e32 v46, 16, v81
	v_and_b32_e32 v47, 0xffff0000, v81
	v_lshlrev_b32_e32 v52, 16, v82
	v_and_b32_e32 v53, 0xffff0000, v82
	v_pk_add_f32 v[38:39], v[38:39], v[46:47]
	v_pk_add_f32 v[36:37], v[36:37], v[44:45]
	v_pk_add_f32 v[46:47], v[32:33], v[52:53]
	v_mul_f32_e32 v32, v37, v37
	v_mul_f32_e32 v33, v39, v39
	v_fmac_f32_e32 v32, v36, v36
	v_fmac_f32_e32 v33, v38, v38
	v_lshlrev_b32_e32 v54, 16, v83
	v_and_b32_e32 v55, 0xffff0000, v83
	v_add_f32_e32 v32, v32, v33
	v_mul_f32_e32 v33, v47, v47
	v_pk_add_f32 v[44:45], v[34:35], v[54:55]
	v_fmac_f32_e32 v33, v46, v46
	v_add_f32_e32 v32, v33, v32
	v_mul_f32_e32 v33, v45, v45
	v_fmac_f32_e32 v33, v44, v44
	v_add_f32_e32 v32, v33, v32
	v_add_f32_e32 v32, v56, v32
	ds_bpermute_b32 v33, v98, v32
	s_waitcnt lgkmcnt(0)
	v_lshl_add_u64 v[48:49], s[44:45], 0, v[100:101]
	v_lshl_add_u64 v[48:49], s[0:1], 1, v[48:49]
	v_lshl_add_u64 v[48:49], v[168:169], 1, v[48:49]
	v_cvt_pk_bf16_f32 v42, v42, v43
	v_add_f32_e32 v32, v32, v33
	ds_bpermute_b32 v33, v116, v32
	v_cvt_pk_bf16_f32 v43, v50, v51
	global_store_dwordx4 v[48:49], v[40:43], off
	v_cvt_pk_bf16_f32 v34, v36, v37
	v_cvt_pk_bf16_f32 v35, v38, v39
	v_cvt_pk_bf16_f32 v36, v46, v47
	v_cvt_pk_bf16_f32 v37, v44, v45
	global_store_dwordx4 v[48:49], v[34:37], off offset:256
	s_and_saveexec_b64 s[6:7], s[4:5]
	s_cbranch_execz .LBB0_904
	s_waitcnt lgkmcnt(0)
	v_add_f32_e32 v32, v32, v33
	v_cndmask_b32_e32 v34, 0, v32, vcc
	s_lshl_b32 s16, s90, 3
	v_lshlrev_b64 v[32:33], 7, v[92:93]
	s_ashr_i32 s17, s16, 31
	v_lshl_add_u64 v[32:33], s[42:43], 0, v[32:33]
	v_lshl_add_u64 v[32:33], s[16:17], 2, v[32:33]
	s_lshl_b32 s52, s91, 2
	v_lshl_add_u64 v[32:33], v[32:33], 0, s[52:53]
	v_lshl_add_u64 v[32:33], v[166:167], 2, v[32:33]
	global_store_dword v[32:33], v34, off
.LBB0_904:
	s_or_b64 exec, exec, s[6:7]
	v_lshlrev_b32_e32 v34, 16, v76
	v_and_b32_e32 v35, 0xffff0000, v76
	v_lshlrev_b32_e32 v36, 16, v77
	v_and_b32_e32 v37, 0xffff0000, v77
	v_lshlrev_b32_e32 v38, 16, v78
	v_and_b32_e32 v39, 0xffff0000, v78
	v_lshlrev_b32_e32 v40, 16, v79
	v_and_b32_e32 v41, 0xffff0000, v79
	v_pk_add_f32 v[30:31], v[30:31], v[36:37]
	v_pk_add_f32 v[28:29], v[28:29], v[34:35]
	v_pk_add_f32 v[34:35], v[26:27], v[40:41]
	v_pk_add_f32 v[26:27], v[24:25], v[38:39]
	v_mul_f32_e32 v24, v29, v29
	v_mul_f32_e32 v25, v31, v31
	v_fmac_f32_e32 v24, v28, v28
	v_fmac_f32_e32 v25, v30, v30
	v_add_f32_e32 v24, v24, v25
	v_mul_f32_e32 v25, v27, v27
	v_fmac_f32_e32 v25, v26, v26
	v_add_f32_e32 v24, v25, v24
	v_mul_f32_e32 v25, v35, v35
	v_fmac_f32_e32 v25, v34, v34
	v_add_f32_e32 v40, v25, v24
	v_cvt_pk_bf16_f32 v24, v28, v29
	v_cvt_pk_bf16_f32 v25, v30, v31
	v_lshlrev_b32_e32 v28, 16, v72
	v_and_b32_e32 v29, 0xffff0000, v72
	v_lshlrev_b32_e32 v30, 16, v73
	v_and_b32_e32 v31, 0xffff0000, v73
	v_lshlrev_b32_e32 v36, 16, v74
	v_and_b32_e32 v37, 0xffff0000, v74
	v_pk_add_f32 v[22:23], v[22:23], v[30:31]
	v_pk_add_f32 v[20:21], v[20:21], v[28:29]
	v_pk_add_f32 v[30:31], v[16:17], v[36:37]
	v_mul_f32_e32 v16, v21, v21
	v_mul_f32_e32 v17, v23, v23
	v_fmac_f32_e32 v16, v20, v20
	v_fmac_f32_e32 v17, v22, v22
	v_lshlrev_b32_e32 v38, 16, v75
	v_and_b32_e32 v39, 0xffff0000, v75
	v_add_f32_e32 v16, v16, v17
	v_mul_f32_e32 v17, v31, v31
	v_pk_add_f32 v[28:29], v[18:19], v[38:39]
	v_fmac_f32_e32 v17, v30, v30
	v_add_f32_e32 v16, v17, v16
	v_mul_f32_e32 v17, v29, v29
	v_fmac_f32_e32 v17, v28, v28
	v_add_f32_e32 v16, v17, v16
	v_add_f32_e32 v16, v40, v16
	ds_bpermute_b32 v17, v98, v16
	s_waitcnt lgkmcnt(0)
	v_lshlrev_b64 v[32:33], 11, v[90:91]
	v_lshl_add_u64 v[32:33], s[44:45], 0, v[32:33]
	v_lshl_add_u64 v[32:33], s[0:1], 1, v[32:33]
	v_lshl_add_u64 v[32:33], v[168:169], 1, v[32:33]
	v_add_f32_e32 v16, v16, v17
	ds_bpermute_b32 v17, v116, v16
	v_cvt_pk_bf16_f32 v26, v26, v27
	v_cvt_pk_bf16_f32 v27, v34, v35
	global_store_dwordx4 v[32:33], v[24:27], off
	v_cvt_pk_bf16_f32 v18, v20, v21
	v_cvt_pk_bf16_f32 v19, v22, v23
	v_cvt_pk_bf16_f32 v20, v30, v31
	v_cvt_pk_bf16_f32 v21, v28, v29
	global_store_dwordx4 v[32:33], v[18:21], off offset:256
	s_and_saveexec_b64 s[6:7], s[4:5]
	s_cbranch_execz .LBB0_906
	s_waitcnt lgkmcnt(0)
	v_add_f32_e32 v16, v16, v17
	v_cndmask_b32_e32 v18, 0, v16, vcc
	s_lshl_b32 s16, s90, 3
	v_lshlrev_b64 v[16:17], 7, v[90:91]
	s_ashr_i32 s17, s16, 31
	v_lshl_add_u64 v[16:17], s[42:43], 0, v[16:17]
	v_lshl_add_u64 v[16:17], s[16:17], 2, v[16:17]
	s_lshl_b32 s52, s91, 2
	v_lshl_add_u64 v[16:17], v[16:17], 0, s[52:53]
	v_lshl_add_u64 v[16:17], v[166:167], 2, v[16:17]
	global_store_dword v[16:17], v18, off
.LBB0_906:
	s_or_b64 exec, exec, s[6:7]
	v_lshlrev_b32_e32 v18, 16, v68
	v_and_b32_e32 v19, 0xffff0000, v68
	v_lshlrev_b32_e32 v20, 16, v69
	v_and_b32_e32 v21, 0xffff0000, v69
	v_lshlrev_b32_e32 v22, 16, v70
	v_and_b32_e32 v23, 0xffff0000, v70
	v_lshlrev_b32_e32 v24, 16, v71
	v_and_b32_e32 v25, 0xffff0000, v71
	v_pk_add_f32 v[14:15], v[14:15], v[20:21]
	v_pk_add_f32 v[12:13], v[12:13], v[18:19]
	v_pk_add_f32 v[18:19], v[10:11], v[24:25]
	v_pk_add_f32 v[10:11], v[8:9], v[22:23]
	v_mul_f32_e32 v8, v13, v13
	v_mul_f32_e32 v9, v15, v15
	v_fmac_f32_e32 v8, v12, v12
	v_fmac_f32_e32 v9, v14, v14
	v_add_f32_e32 v8, v8, v9
	v_mul_f32_e32 v9, v11, v11
	v_fmac_f32_e32 v9, v10, v10
	v_add_f32_e32 v8, v9, v8
	v_mul_f32_e32 v9, v19, v19
	v_fmac_f32_e32 v9, v18, v18
	v_add_f32_e32 v24, v9, v8
	v_cvt_pk_bf16_f32 v8, v12, v13
	v_cvt_pk_bf16_f32 v9, v14, v15
	v_lshlrev_b32_e32 v12, 16, v64
	v_and_b32_e32 v13, 0xffff0000, v64
	v_lshlrev_b32_e32 v14, 16, v65
	v_and_b32_e32 v15, 0xffff0000, v65
	v_lshlrev_b32_e32 v20, 16, v66
	v_and_b32_e32 v21, 0xffff0000, v66
	v_pk_add_f32 v[6:7], v[6:7], v[14:15]
	v_pk_add_f32 v[4:5], v[4:5], v[12:13]
	v_pk_add_f32 v[14:15], v[0:1], v[20:21]
	v_mul_f32_e32 v0, v5, v5
	v_mul_f32_e32 v1, v7, v7
	v_fmac_f32_e32 v0, v4, v4
	v_fmac_f32_e32 v1, v6, v6
	v_lshlrev_b32_e32 v22, 16, v67
	v_and_b32_e32 v23, 0xffff0000, v67
	v_add_f32_e32 v0, v0, v1
	v_mul_f32_e32 v1, v15, v15
	v_pk_add_f32 v[12:13], v[2:3], v[22:23]
	v_fmac_f32_e32 v1, v14, v14
	v_add_f32_e32 v0, v1, v0
	v_mul_f32_e32 v1, v13, v13
	v_fmac_f32_e32 v1, v12, v12
	v_add_f32_e32 v0, v1, v0
	v_add_f32_e32 v0, v24, v0
	ds_bpermute_b32 v1, v98, v0
	s_waitcnt lgkmcnt(0)
	v_lshlrev_b64 v[16:17], 11, v[88:89]
	v_lshl_add_u64 v[16:17], s[44:45], 0, v[16:17]
	v_lshl_add_u64 v[16:17], s[0:1], 1, v[16:17]
	v_lshl_add_u64 v[16:17], v[168:169], 1, v[16:17]
	v_add_f32_e32 v0, v0, v1
	ds_bpermute_b32 v1, v116, v0
	v_cvt_pk_bf16_f32 v10, v10, v11
	v_cvt_pk_bf16_f32 v11, v18, v19
	global_store_dwordx4 v[16:17], v[8:11], off
	v_cvt_pk_bf16_f32 v2, v4, v5
	v_cvt_pk_bf16_f32 v3, v6, v7
	v_cvt_pk_bf16_f32 v4, v14, v15
	v_cvt_pk_bf16_f32 v5, v12, v13
	global_store_dwordx4 v[16:17], v[2:5], off offset:256
	s_and_saveexec_b64 s[0:1], s[4:5]
	s_cbranch_execz .LBB0_908
	s_waitcnt lgkmcnt(0)
	v_add_f32_e32 v0, v0, v1
	v_cndmask_b32_e32 v2, 0, v0, vcc
	s_lshl_b32 s4, s90, 3
	v_lshlrev_b64 v[0:1], 7, v[88:89]
	s_ashr_i32 s5, s4, 31
	v_lshl_add_u64 v[0:1], s[42:43], 0, v[0:1]
	v_lshl_add_u64 v[0:1], s[4:5], 2, v[0:1]
	s_lshl_b32 s52, s91, 2
	v_lshl_add_u64 v[0:1], v[0:1], 0, s[52:53]
	v_lshl_add_u64 v[0:1], v[166:167], 2, v[0:1]
	global_store_dword v[0:1], v2, off

.LBB0_1119:
	v_lshl_add_u64 v[32:33], s[24:25], 1, v[46:47]
	v_lshlrev_b32_e32 v98, 11, v70
	v_lshl_add_u64 v[72:73], v[32:33], 0, v[98:99]
	global_load_dwordx2 v[74:75], v[72:73], off
	global_load_dwordx2 v[76:77], v[72:73], off offset:256
	v_add_co_u32_e32 v34, vcc, 0x8000, v72
	s_lshl_b32 s4, s45, 3
	s_nop 0
	v_addc_co_u32_e32 v35, vcc, 0, v73, vcc
	global_load_dwordx2 v[66:67], v[34:35], off
	global_load_dwordx2 v[64:65], v[34:35], off offset:256
	v_add_co_u32_e32 v34, vcc, 0x10000, v72
	s_ashr_i32 s5, s4, 31
	s_nop 0
	v_addc_co_u32_e32 v35, vcc, 0, v73, vcc
	global_load_dwordx2 v[62:63], v[34:35], off
	global_load_dwordx2 v[60:61], v[34:35], off offset:256
	v_add_co_u32_e32 v34, vcc, 0x18000, v72
	s_lshl_b64 s[4:5], s[4:5], 2
	s_nop 0
	v_addc_co_u32_e32 v35, vcc, 0, v73, vcc
	global_load_dwordx2 v[58:59], v[34:35], off
	s_nop 0
	global_load_dwordx2 v[34:35], v[34:35], off offset:256
	s_add_u32 s4, s42, s4
	s_addc_u32 s5, s43, s5
	s_waitcnt vmcnt(0)
	v_lshlrev_b32_e32 v78, 16, v74
	v_and_b32_e32 v79, 0xffff0000, v74
	v_pk_add_f32 v[24:25], v[24:25], v[78:79]
	v_lshlrev_b32_e32 v74, 16, v75
	v_and_b32_e32 v75, 0xffff0000, v75
	v_mul_f32_e32 v71, v25, v25
	v_pk_add_f32 v[26:27], v[26:27], v[74:75]
	v_fmac_f32_e32 v71, v24, v24
	v_cvt_pk_bf16_f32 v24, v24, v25
	v_cvt_pk_bf16_f32 v25, v26, v27
	global_store_dwordx2 v[72:73], v[24:25], off
	v_lshlrev_b32_e32 v24, 16, v76
	v_and_b32_e32 v25, 0xffff0000, v76
	v_mul_f32_e32 v74, v27, v27
	v_pk_add_f32 v[24:25], v[28:29], v[24:25]
	v_fmac_f32_e32 v74, v26, v26
	v_lshlrev_b32_e32 v26, 16, v77
	v_and_b32_e32 v27, 0xffff0000, v77
	v_mul_f32_e32 v28, v25, v25
	v_pk_add_f32 v[26:27], v[30:31], v[26:27]
	v_fmac_f32_e32 v28, v24, v24
	v_cvt_pk_bf16_f32 v24, v24, v25
	v_cvt_pk_bf16_f32 v25, v26, v27
	global_store_dwordx2 v[72:73], v[24:25], off offset:256
	v_and_b32_e32 v25, 64, v214
	v_mul_f32_e32 v29, v27, v27
	v_xor_b32_e32 v24, 16, v214
	v_add_u32_e32 v25, 64, v25
	v_fmac_f32_e32 v29, v26, v26
	v_cmp_lt_i32_e32 vcc, v24, v25
	v_add_f32_e32 v71, v71, v74
	v_add_f32_e32 v28, v28, v29
	v_cndmask_b32_e32 v24, v214, v24, vcc
	v_add_f32_e32 v28, v71, v28
	v_lshlrev_b32_e32 v24, 2, v24
	ds_bpermute_b32 v26, v24, v28
	v_xor_b32_e32 v27, 32, v214
	v_cmp_lt_i32_e32 vcc, v27, v25
	s_waitcnt lgkmcnt(0)
	v_add_f32_e32 v26, v28, v26
	v_cndmask_b32_e32 v25, v214, v27, vcc
	v_lshlrev_b32_e32 v25, 2, v25
	ds_bpermute_b32 v27, v25, v26
	s_and_saveexec_b64 s[24:25], s[2:3]
	s_cbranch_execz .LBB0_1121
	v_lshlrev_b32_e32 v98, 5, v70
	s_waitcnt lgkmcnt(0)
	v_add_f32_e32 v28, v26, v27
	v_lshl_add_u64 v[26:27], v[98:99], 2, s[4:5]
	global_store_dword v[26:27], v28, off
.LBB0_1121:
	s_or_b64 exec, exec, s[24:25]
	v_lshlrev_b32_e32 v28, 16, v66
	v_and_b32_e32 v29, 0xffff0000, v66
	v_lshlrev_b32_e32 v30, 16, v67
	v_and_b32_e32 v31, 0xffff0000, v67
	v_pk_add_f32 v[18:19], v[18:19], v[30:31]
	v_pk_add_f32 v[16:17], v[16:17], v[28:29]
	v_mul_f32_e32 v28, v19, v19
	s_waitcnt lgkmcnt(0)
	v_mul_f32_e32 v27, v17, v17
	v_fmac_f32_e32 v27, v16, v16
	v_fmac_f32_e32 v28, v18, v18
	v_add_f32_e32 v27, v27, v28
	v_lshlrev_b32_e32 v28, 16, v64
	v_and_b32_e32 v29, 0xffff0000, v64
	v_lshlrev_b32_e32 v30, 16, v65
	v_and_b32_e32 v31, 0xffff0000, v65
	v_pk_add_f32 v[22:23], v[22:23], v[30:31]
	v_pk_add_f32 v[20:21], v[20:21], v[28:29]
	v_mul_f32_e32 v29, v23, v23
	v_mul_f32_e32 v28, v21, v21
	v_fmac_f32_e32 v28, v20, v20
	v_fmac_f32_e32 v29, v22, v22
	v_add_f32_e32 v28, v28, v29
	v_add_f32_e32 v27, v27, v28
	ds_bpermute_b32 v64, v24, v27
	v_cvt_pk_bf16_f32 v30, v16, v17
	v_or_b32_e32 v26, 16, v70
	v_lshlrev_b32_e32 v98, 11, v26
	v_lshl_add_u64 v[28:29], v[32:33], 0, v[98:99]
	s_waitcnt lgkmcnt(0)
	v_add_f32_e32 v16, v27, v64
	ds_bpermute_b32 v17, v25, v16
	v_cvt_pk_bf16_f32 v31, v18, v19
	global_store_dwordx2 v[28:29], v[30:31], off
	v_cvt_pk_bf16_f32 v18, v20, v21
	v_cvt_pk_bf16_f32 v19, v22, v23
	global_store_dwordx2 v[28:29], v[18:19], off offset:256
	s_and_saveexec_b64 s[24:25], s[2:3]
	s_cbranch_execz .LBB0_1123
	v_lshlrev_b32_e32 v98, 5, v26
	s_waitcnt lgkmcnt(0)
	v_add_f32_e32 v18, v16, v17
	v_lshl_add_u64 v[16:17], v[98:99], 2, s[4:5]
	global_store_dword v[16:17], v18, off
.LBB0_1123:
	s_or_b64 exec, exec, s[24:25]
	v_lshlrev_b32_e32 v18, 16, v62
	v_and_b32_e32 v19, 0xffff0000, v62
	v_lshlrev_b32_e32 v20, 16, v63
	v_and_b32_e32 v21, 0xffff0000, v63
	v_pk_add_f32 v[10:11], v[10:11], v[20:21]
	v_pk_add_f32 v[8:9], v[8:9], v[18:19]
	v_mul_f32_e32 v18, v11, v11
	s_waitcnt lgkmcnt(0)
	v_mul_f32_e32 v17, v9, v9
	v_fmac_f32_e32 v17, v8, v8
	v_fmac_f32_e32 v18, v10, v10
	v_add_f32_e32 v17, v17, v18
	v_lshlrev_b32_e32 v18, 16, v60
	v_and_b32_e32 v19, 0xffff0000, v60
	v_lshlrev_b32_e32 v20, 16, v61
	v_and_b32_e32 v21, 0xffff0000, v61
	v_pk_add_f32 v[14:15], v[14:15], v[20:21]
	v_pk_add_f32 v[12:13], v[12:13], v[18:19]
	v_mul_f32_e32 v19, v15, v15
	v_mul_f32_e32 v18, v13, v13
	v_fmac_f32_e32 v18, v12, v12
	v_fmac_f32_e32 v19, v14, v14
	v_add_f32_e32 v18, v18, v19
	v_add_f32_e32 v17, v17, v18
	ds_bpermute_b32 v22, v24, v17
	v_cvt_pk_bf16_f32 v20, v8, v9
	v_or_b32_e32 v16, 32, v70
	v_lshlrev_b32_e32 v98, 11, v16
	v_lshl_add_u64 v[18:19], v[32:33], 0, v[98:99]
	s_waitcnt lgkmcnt(0)
	v_add_f32_e32 v8, v17, v22
	ds_bpermute_b32 v9, v25, v8
	v_cvt_pk_bf16_f32 v21, v10, v11
	global_store_dwordx2 v[18:19], v[20:21], off
	v_cvt_pk_bf16_f32 v10, v12, v13
	v_cvt_pk_bf16_f32 v11, v14, v15
	global_store_dwordx2 v[18:19], v[10:11], off offset:256
	s_and_saveexec_b64 s[24:25], s[2:3]
	s_cbranch_execz .LBB0_1125
	v_lshlrev_b32_e32 v98, 5, v16
	s_waitcnt lgkmcnt(0)
	v_add_f32_e32 v10, v8, v9
	v_lshl_add_u64 v[8:9], v[98:99], 2, s[4:5]
	global_store_dword v[8:9], v10, off
.LBB0_1125:
	s_or_b64 exec, exec, s[24:25]
	v_lshlrev_b32_e32 v10, 16, v58
	v_and_b32_e32 v11, 0xffff0000, v58
	v_lshlrev_b32_e32 v12, 16, v59
	v_and_b32_e32 v13, 0xffff0000, v59
	v_pk_add_f32 v[2:3], v[2:3], v[12:13]
	v_pk_add_f32 v[0:1], v[0:1], v[10:11]
	v_mul_f32_e32 v10, v3, v3
	s_waitcnt lgkmcnt(0)
	v_mul_f32_e32 v9, v1, v1
	v_fmac_f32_e32 v9, v0, v0
	v_fmac_f32_e32 v10, v2, v2
	v_add_f32_e32 v9, v9, v10
	v_lshlrev_b32_e32 v10, 16, v34
	v_and_b32_e32 v11, 0xffff0000, v34
	v_lshlrev_b32_e32 v12, 16, v35
	v_and_b32_e32 v13, 0xffff0000, v35
	v_pk_add_f32 v[6:7], v[6:7], v[12:13]
	v_pk_add_f32 v[4:5], v[4:5], v[10:11]
	v_mul_f32_e32 v11, v7, v7
	v_mul_f32_e32 v10, v5, v5
	v_fmac_f32_e32 v10, v4, v4
	v_fmac_f32_e32 v11, v6, v6
	v_add_f32_e32 v10, v10, v11
	v_add_f32_e32 v9, v9, v10
	ds_bpermute_b32 v14, v24, v9
	v_cvt_pk_bf16_f32 v12, v0, v1
	v_or_b32_e32 v8, 48, v70
	v_lshlrev_b32_e32 v98, 11, v8
	v_lshl_add_u64 v[10:11], v[32:33], 0, v[98:99]
	s_waitcnt lgkmcnt(0)
	v_add_f32_e32 v0, v9, v14
	ds_bpermute_b32 v1, v25, v0
	v_cvt_pk_bf16_f32 v13, v2, v3
	global_store_dwordx2 v[10:11], v[12:13], off
	v_cvt_pk_bf16_f32 v2, v4, v5
	v_cvt_pk_bf16_f32 v3, v6, v7
	global_store_dwordx2 v[10:11], v[2:3], off offset:256
	s_and_saveexec_b64 s[24:25], s[2:3]
	s_cbranch_execz .LBB0_934
	v_lshlrev_b32_e32 v98, 5, v8
	s_waitcnt lgkmcnt(0)
	v_add_f32_e32 v2, v0, v1
	v_lshl_add_u64 v[0:1], v[98:99], 2, s[4:5]
	global_store_dword v[0:1], v2, off
	s_branch .LBB0_934

.LBB0_1154:
	v_add_u32_e32 v18, s29, v20
	v_ashrrev_i32_e32 v19, 31, v18
	v_lshl_add_u64 v[16:17], s[10:11], 1, v[10:11]
	v_lshlrev_b64 v[28:29], 11, v[18:19]
	v_lshl_add_u64 v[28:29], v[16:17], 0, v[28:29]
	global_load_dwordx2 v[30:31], v[28:29], off
	v_or_b32_e32 v18, 16, v18
	v_ashrrev_i32_e32 v19, 31, v18
	v_lshlrev_b64 v[18:19], 11, v[18:19]
	v_lshl_add_u64 v[18:19], v[16:17], 0, v[18:19]
	global_load_dwordx2 v[18:19], v[18:19], off
	s_waitcnt vmcnt(0)
	v_lshlrev_b32_e32 v32, 16, v30
	v_and_b32_e32 v33, 0xffff0000, v30
	v_pk_add_f32 v[4:5], v[4:5], v[32:33]
	v_lshlrev_b32_e32 v30, 16, v31
	v_and_b32_e32 v31, 0xffff0000, v31
	v_mul_f32_e32 v27, v5, v5
	v_pk_add_f32 v[6:7], v[6:7], v[30:31]
	v_fmac_f32_e32 v27, v4, v4
	v_cvt_pk_bf16_f32 v4, v4, v5
	v_cvt_pk_bf16_f32 v5, v6, v7
	global_store_dwordx2 v[28:29], v[4:5], off
	v_and_b32_e32 v5, 64, v214
	v_xor_b32_e32 v4, 16, v214
	v_add_u32_e32 v5, 64, v5
	v_mul_f32_e32 v30, v7, v7
	v_cmp_lt_i32_e32 vcc, v4, v5
	v_fmac_f32_e32 v30, v6, v6
	v_add_f32_e32 v27, v27, v30
	v_cndmask_b32_e32 v4, v214, v4, vcc
	v_lshlrev_b32_e32 v4, 2, v4
	ds_bpermute_b32 v6, v4, v27
	v_xor_b32_e32 v7, 32, v214
	v_cmp_lt_i32_e32 vcc, v7, v5
	s_waitcnt lgkmcnt(0)
	v_add_f32_e32 v6, v27, v6
	v_cndmask_b32_e32 v5, v214, v7, vcc
	v_lshlrev_b32_e32 v5, 2, v5
	ds_bpermute_b32 v7, v5, v6
	s_and_saveexec_b64 s[6:7], s[2:3]
	s_cbranch_execz .LBB0_1156
	s_waitcnt lgkmcnt(0)
	v_add_f32_e32 v6, v6, v7
	ds_write_b32 v24, v6
.LBB0_1156:
	s_or_b64 exec, exec, s[6:7]
	v_lshlrev_b32_e32 v6, 16, v18
	s_waitcnt lgkmcnt(0)
	v_and_b32_e32 v7, 0xffff0000, v18
	v_lshlrev_b32_e32 v18, 16, v19
	v_and_b32_e32 v19, 0xffff0000, v19
	v_pk_add_f32 v[2:3], v[2:3], v[18:19]
	v_pk_add_f32 v[6:7], v[0:1], v[6:7]
	v_mul_f32_e32 v1, v3, v3
	v_mul_f32_e32 v0, v7, v7
	v_fmac_f32_e32 v0, v6, v6
	v_fmac_f32_e32 v1, v2, v2
	v_add_f32_e32 v27, v0, v1
	ds_bpermute_b32 v4, v4, v27
	v_add_u32_e32 v0, s29, v23
	v_ashrrev_i32_e32 v1, 31, v0
	v_lshlrev_b64 v[18:19], 11, v[0:1]
	v_cvt_pk_bf16_f32 v6, v6, v7
	s_waitcnt lgkmcnt(0)
	v_add_f32_e32 v0, v27, v4
	ds_bpermute_b32 v1, v5, v0
	v_lshl_add_u64 v[4:5], v[16:17], 0, v[18:19]
	v_cvt_pk_bf16_f32 v7, v2, v3
	global_store_dwordx2 v[4:5], v[6:7], off
	s_and_saveexec_b64 s[6:7], s[2:3]
	s_cbranch_execz .LBB0_1158
	s_waitcnt lgkmcnt(0)
	v_add_f32_e32 v0, v0, v1
	ds_write_b32 v25, v0
